# diff tile loop stagger with a shorter delay: waves 4-7 sleep 128 cycles after each tile barrier
# speedup vs baseline: 1.0090x; 1.0021x over previous
.LBB0_475:
	s_cmp_lt_u32 s99, 2
	s_cbranch_scc1 .Ldf_nosleep
	s_sleep 2
